# v61 variant: XCD leader issues its L2 invalidate right after the completed L2 write-back (overlaps the TOP atomic / TOPGEN wait; all workgroups of the XCD are inside the barrier so the L2 cannot refil
# speedup vs baseline: 1.0261x; 1.0013x over previous
; __device__ __forceinline__ unsigned xb_ld(unsigned* p)              { return __hip_atomic_load(p, __ATOMIC_RELAXED, __HIP_MEMORY_SCOPE_AGENT); }
; __device__ __forceinline__ unsigned xb_add(unsigned* p, unsigned v) { return __hip_atomic_fetch_add(p, v, __ATOMIC_RELAXED, __HIP_MEMORY_SCOPE_AGENT); }
; #define XB_SPIN(cond, bar) do { unsigned _sp = 0; while (cond) { __builtin_amdgcn_s_sleep(1); \
;     if ((++_sp & 255u) == 0u) { if (xb_ld(&(bar)[XB_TMO])) break; if (_sp > XB_SPIN_CAP) { atomicAdd(&(bar)[XB_TMO], 1u); break; } } } } while (0)
; __device__ __forceinline__ void xcd_barrier(const XcdBarrier& b) {
;     ...
;         const unsigned old = xb_add(&bar[XB_XSUB(b.x)], 1u);
;         const unsigned gen = old / nloc;
;         if (old + 1u == (gen + 1u) * nloc) {
;             __builtin_amdgcn_fence(__ATOMIC_RELEASE, "agent");
;             asm volatile("s_waitcnt vmcnt(0)" ::: "memory");
;             const unsigned og = xb_add(&bar[XB_TOP], 1u);
;             const unsigned tg = og / nx;
;             if (og + 1u == (tg + 1u) * nx) xb_add(&bar[XB_TOPGEN], 1u);
;             else XB_SPIN(xb_ld(&bar[XB_TOPGEN]) == tg, bar);
;             __builtin_amdgcn_fence(__ATOMIC_ACQUIRE, "agent");
;             xb_add(&bar[XB_XGEN(b.x)], 1u);
;             asm volatile("s_waitcnt vmcnt(0)" ::: "memory");
.LBB0_162:
	s_andn2_saveexec_b64 s[0:1], s[6:7]
	s_cbranch_execz .LBB0_180
	s_mov_b64 s[6:7], exec
	buffer_wbl2 sc1
	s_waitcnt lgkmcnt(0)
	s_waitcnt vmcnt(0)
	buffer_inv sc1
	v_mbcnt_lo_u32_b32 v2, s6, 0
	v_mbcnt_hi_u32_b32 v2, s7, v2
	v_cmp_eq_u32_e32 vcc, 0, v2
	s_and_saveexec_b64 s[28:29], vcc
	s_cbranch_execz .LBB0_165
	s_bcnt1_i32_b64 s0, s[6:7]
	v_mov_b32_e32 v3, 0x7000
	v_mov_b32_e32 v4, s0
	global_atomic_add v3, v3, v4, s[26:27] offset:1024 sc0

; __device__ __forceinline__ unsigned xb_add(unsigned* p, unsigned v) { return __hip_atomic_fetch_add(p, v, __ATOMIC_RELAXED, __HIP_MEMORY_SCOPE_AGENT); }
; __device__ __forceinline__ void xcd_barrier(const XcdBarrier& b) {
;     ...
;             __builtin_amdgcn_fence(__ATOMIC_ACQUIRE, "agent");
;             xb_add(&bar[XB_XGEN(b.x)], 1u);
;             asm volatile("s_waitcnt vmcnt(0)" ::: "memory");
.LBB0_179:
	s_or_b64 exec, exec, s[6:7]
	v_mov_b32_e32 v1, 0x2000
	v_mov_b32_e32 v2, 1
	s_waitcnt vmcnt(0)
	buffer_inv sc0
	global_atomic_add v1, v2, s[4:5] offset:1024
	s_waitcnt vmcnt(0)

; __device__ __forceinline__ unsigned xb_ld(unsigned* p)              { return __hip_atomic_load(p, __ATOMIC_RELAXED, __HIP_MEMORY_SCOPE_AGENT); }
; __device__ __forceinline__ unsigned xb_add(unsigned* p, unsigned v) { return __hip_atomic_fetch_add(p, v, __ATOMIC_RELAXED, __HIP_MEMORY_SCOPE_AGENT); }
; #define XB_SPIN(cond, bar) do { unsigned _sp = 0; while (cond) { __builtin_amdgcn_s_sleep(1); \
;     if ((++_sp & 255u) == 0u) { if (xb_ld(&(bar)[XB_TMO])) break; if (_sp > XB_SPIN_CAP) { atomicAdd(&(bar)[XB_TMO], 1u); break; } } } } while (0)
; __device__ __forceinline__ void xcd_barrier(const XcdBarrier& b) {
;     ...
;         const unsigned old = xb_add(&bar[XB_XSUB(b.x)], 1u);
;         const unsigned gen = old / nloc;
;         if (old + 1u == (gen + 1u) * nloc) {
;             __builtin_amdgcn_fence(__ATOMIC_RELEASE, "agent");
;             asm volatile("s_waitcnt vmcnt(0)" ::: "memory");
;             const unsigned og = xb_add(&bar[XB_TOP], 1u);
;             const unsigned tg = og / nx;
;             if (og + 1u == (tg + 1u) * nx) xb_add(&bar[XB_TOPGEN], 1u);
;             else XB_SPIN(xb_ld(&bar[XB_TOPGEN]) == tg, bar);
;             __builtin_amdgcn_fence(__ATOMIC_ACQUIRE, "agent");
;             xb_add(&bar[XB_XGEN(b.x)], 1u);
;             asm volatile("s_waitcnt vmcnt(0)" ::: "memory");
.LBB0_559:
	s_andn2_saveexec_b64 s[0:1], s[6:7]
	s_cbranch_execz .LBB0_577
	s_mov_b64 s[6:7], exec
	buffer_wbl2 sc1
	s_waitcnt lgkmcnt(0)
	s_waitcnt vmcnt(0)
	buffer_inv sc1
	v_mbcnt_lo_u32_b32 v2, s6, 0
	v_mbcnt_hi_u32_b32 v2, s7, v2
	v_cmp_eq_u32_e32 vcc, 0, v2
	s_and_saveexec_b64 s[8:9], vcc
	s_cbranch_execz .LBB0_562
	s_bcnt1_i32_b64 s0, s[6:7]
	v_mov_b32_e32 v3, 0x7000
	v_mov_b32_e32 v4, s0
	global_atomic_add v3, v3, v4, s[26:27] offset:1024 sc0
